# epilogue split (T22) + gate loads issued at tail-stage entry into v230-245 so their latency is hidden
# speedup vs baseline: 1.0036x; 1.0036x over previous
; #define LAS __attribute__((address_space(3)))
; #define MFMA32(a, b, c) __builtin_amdgcn_mfma_f32_32x32x16_bf16((a), (b), (c), 0, 0, 0)
; DI void attn_unit(const Params& p, int b, int h, int qb, LAS unsigned char* lds, int tid, int lane, int wave) {
;     ...
;         const int kb = st * 64 + g * 32;
;         if (kb <= qr0 + 31) {
;             f32x16 s;
; #pragma unroll
;             for (int j = 0; j < 16; ++j) s[j] = 0.f;
;             const LAS unsigned char* kp = lds + AT_K0 + buf * AT_KB + (g * 32 + r) * 400 + hh * 16;
;             bf16x8 kf[12];
; #pragma unroll
;             for (int kk = 0; kk < 12; ++kk) kf[kk] = *(const LAS bf16x8*)(kp + kk * 32);
;             __builtin_amdgcn_sched_barrier(0);
;             __builtin_amdgcn_s_setprio(1);
; #pragma unroll
;             for (int kk = 0; kk < 12; ++kk) s = MFMA32(kf[kk], qf[kk], s);
;             __builtin_amdgcn_s_setprio(0);
;             const LAS unsigned char* vp = lds + AT_V0 + buf * AT_VB + r * 136 + (g * 32 + 4 * hh) * 2;
;             bf16x8 vf[2][4];
; #pragma unroll
;             for (int ks = 0; ks < 2; ++ks)
; #pragma unroll
;                 for (int blk = 0; blk < 4; ++blk) {
;                     const s16x4 lo = *(const LAS s16x4*)(vp + blk * 32 * 136 + ks * 32), hi = *(const LAS s16x4*)(vp + blk * 32 * 136 + ks * 32 + 16);
;                     vf[ks][blk] = __builtin_shufflevector(lo, hi, 0, 1, 2, 3, 4, 5, 6, 7);
;                 }
;             __builtin_amdgcn_sched_barrier(0);
;             if (kb + 31 > qr0) {
;                 const int qa = qr0 + r - kb - 4 * hh;
; #pragma unroll
;                 for (int j = 0; j < 16; ++j) if ((j & 3) + 8 * (j >> 2) > qa) s[j] = -INFINITY;
;     ...
;         const bf16_t* gp = Z + tok * ZLD + Z_MG + h * 128 + 4 * hh;
;         bf16_t* op = OB + tok * DM + 512 + h * 128 + 4 * hh;
;         u32x2 gw[4][4];
; #pragma unroll
;         for (int i = 0; i < 4; ++i)
; #pragma unroll
;             for (int q = 0; q < 4; ++q) gw[i][q] = *(const u32x2*)(gp + i * 32 + q * 8);
.LBB0_434:
	v_lshlrev_b32_e32 v246, 12, v202
	s_lshl_b32 s0, s2, 8
	s_lshl_b32 s1, s21, 7
	s_add_u32 s0, s0, s1
	s_add_u32 s0, s0, 0x4600c00
	s_mov_b32 s1, s93
	v_lshl_add_u32 v246, v182, 1, v246
	v_mov_b32_e32 v247, 0
	v_lshl_add_u64 v[250:251], v[246:247], 0, s[50:51]
	v_lshl_add_u64 v[250:251], v[250:251], 0, s[0:1]
	global_load_dwordx2 v[230:231], v[250:251], off
	global_load_dwordx2 v[232:233], v[250:251], off offset:16
	global_load_dwordx2 v[234:235], v[250:251], off offset:32
	global_load_dwordx2 v[236:237], v[250:251], off offset:48
	global_load_dwordx2 v[238:239], v[250:251], off offset:64
	global_load_dwordx2 v[240:241], v[250:251], off offset:80
	global_load_dwordx2 v[242:243], v[250:251], off offset:96
	global_load_dwordx2 v[244:245], v[250:251], off offset:112
	s_add_i32 s59, s59, s56
	s_cmp_gt_i32 s59, s57
	s_cbranch_scc1 .LBB0_440
	s_and_b32 s0, s63, 1
	s_mul_i32 s1, s0, 0x6400
	v_add_u32_e32 v0, s1, v216
	ds_read_b128 v[66:69], v0
	ds_read_b128 v[130:133], v0 offset:32
	ds_read_b128 v[134:137], v0 offset:64
	ds_read_b128 v[138:141], v0 offset:96
	ds_read_b128 v[142:145], v0 offset:128
	ds_read_b128 v[146:149], v0 offset:160
	ds_read_b128 v[150:153], v0 offset:192
	ds_read_b128 v[154:157], v0 offset:224
	ds_read_b128 v[158:161], v0 offset:256
	ds_read_b128 v[162:165], v0 offset:288
	ds_read_b128 v[166:169], v0 offset:320
	ds_read_b128 v[170:173], v0 offset:352
	s_setprio 1
	s_setprio 0
	s_waitcnt lgkmcnt(11)
	v_mfma_f32_32x32x16_bf16 v[66:81], v[66:69], v[126:129], 0
	s_mulk_i32 s0, 0x4800
	v_add_u32_e32 v0, s0, v206
	s_waitcnt lgkmcnt(10)
	v_mfma_f32_32x32x16_bf16 v[66:81], v[130:133], v[122:125], v[66:81]
	s_waitcnt lgkmcnt(9)
	v_mfma_f32_32x32x16_bf16 v[66:81], v[134:137], v[118:121], v[66:81]
	s_waitcnt lgkmcnt(8)
	v_mfma_f32_32x32x16_bf16 v[66:81], v[138:141], v[114:117], v[66:81]
	s_waitcnt lgkmcnt(7)
	v_mfma_f32_32x32x16_bf16 v[66:81], v[142:145], v[110:113], v[66:81]
	s_waitcnt lgkmcnt(6)
	v_mfma_f32_32x32x16_bf16 v[66:81], v[146:149], v[106:109], v[66:81]
	s_waitcnt lgkmcnt(5)
	v_mfma_f32_32x32x16_bf16 v[66:81], v[150:153], v[102:105], v[66:81]
	s_waitcnt lgkmcnt(4)
	v_mfma_f32_32x32x16_bf16 v[66:81], v[154:157], v[98:101], v[66:81]
	s_waitcnt lgkmcnt(3)
	v_mfma_f32_32x32x16_bf16 v[66:81], v[158:161], v[94:97], v[66:81]
	s_waitcnt lgkmcnt(2)
	v_mfma_f32_32x32x16_bf16 v[66:81], v[162:165], v[90:93], v[66:81]
	ds_read_b128 v[102:105], v0 offset:51200
	ds_read_b128 v[90:93], v0 offset:51232
	ds_read_b128 v[106:109], v0 offset:55808
	s_waitcnt lgkmcnt(4)
	v_mfma_f32_32x32x16_bf16 v[66:81], v[166:169], v[86:89], v[66:81]
	ds_read_b128 v[114:117], v0 offset:60416
	ds_read_b128 v[110:113], v0 offset:65024
	ds_read_b128 v[98:101], v0 offset:55840
	ds_read_b128 v[94:97], v0 offset:60448
	ds_read_b128 v[86:89], v0 offset:65056
	s_waitcnt lgkmcnt(8)
	v_mfma_f32_32x32x16_bf16 v[66:81], v[170:173], v[82:85], v[66:81]
	s_or_b32 s0, s59, 31
	s_cmp_le_i32 s0, s36
	s_cbranch_scc1 .LBB0_437
	v_add_u32_e32 v0, s59, v182
	v_sub_u32_e32 v0, v205, v0
	v_cmp_gt_i32_e64 s[30:31], 26, v0
	v_cmp_gt_i32_e64 s[34:35], 27, v0
	v_cmp_gt_i32_e64 s[28:29], 25, v0
	s_and_b64 s[30:31], s[34:35], s[30:31]
	v_cmp_gt_i32_e64 s[26:27], 24, v0
	s_and_b64 s[28:29], s[30:31], s[28:29]
	v_cmp_gt_i32_e64 s[24:25], 19, v0
	s_and_b64 s[26:27], s[28:29], s[26:27]
	v_cmp_gt_i32_e64 s[22:23], 18, v0
	s_and_b64 s[24:25], s[26:27], s[24:25]
	v_cmp_gt_i32_e64 s[18:19], 17, v0
	s_and_b64 s[22:23], s[24:25], s[22:23]
	v_cmp_gt_i32_e64 s[16:17], 16, v0
	s_and_b64 s[18:19], s[22:23], s[18:19]
	v_cmp_gt_i32_e64 s[14:15], 11, v0
	s_and_b64 s[16:17], s[18:19], s[16:17]
	v_cmp_gt_i32_e64 s[12:13], 10, v0
	s_and_b64 s[14:15], s[16:17], s[14:15]
	v_cmp_gt_i32_e64 s[10:11], 9, v0
	s_and_b64 s[12:13], s[14:15], s[12:13]
	v_cmp_gt_i32_e64 s[8:9], 8, v0
	s_and_b64 s[10:11], s[12:13], s[10:11]
	v_cmp_gt_i32_e64 s[6:7], 3, v0
	s_and_b64 s[8:9], s[10:11], s[8:9]
	v_cmp_gt_i32_e64 s[4:5], 2, v0
	s_and_b64 s[6:7], s[8:9], s[6:7]
	v_cmp_gt_i32_e64 s[0:1], 1, v0
	s_and_b64 s[4:5], s[6:7], s[4:5]
	v_cmp_gt_i32_e32 vcc, 0, v0
	s_and_b64 s[0:1], s[4:5], s[0:1]
	s_and_b64 vcc, s[0:1], vcc
	v_cndmask_b32_e64 v81, v81, v229, s[34:35]
	v_cndmask_b32_e64 v80, v80, v229, s[30:31]
	v_cndmask_b32_e64 v79, v79, v229, s[28:29]
	v_cndmask_b32_e64 v78, v78, v229, s[26:27]
	v_cndmask_b32_e64 v77, v77, v229, s[24:25]
	v_cndmask_b32_e64 v76, v76, v229, s[22:23]
	v_cndmask_b32_e64 v75, v75, v229, s[18:19]
	v_cndmask_b32_e64 v74, v74, v229, s[16:17]
	v_cndmask_b32_e64 v73, v73, v229, s[14:15]
	v_cndmask_b32_e64 v72, v72, v229, s[12:13]
	v_cndmask_b32_e64 v71, v71, v229, s[10:11]
	v_cndmask_b32_e64 v70, v70, v229, s[8:9]
	v_cndmask_b32_e64 v69, v69, v229, s[6:7]
	v_cndmask_b32_e64 v68, v68, v229, s[4:5]
	v_cndmask_b32_e64 v67, v67, v229, s[0:1]
	v_cndmask_b32_e32 v66, v66, v229, vcc

; DI unsigned pk2(float lo, float hi) { f32x2 v = {lo, hi}; return __builtin_bit_cast(unsigned, __builtin_convertvector(v, bf2_t)); }
; DI float bflo(unsigned w) { return __uint_as_float(w << 16); }
; DI float bfhi(unsigned w) { return __uint_as_float(w & 0xffff0000u); }
; DI void attn_unit(const Params& p, int b, int h, int qb, LAS unsigned char* lds, int tid, int lane, int wave) {
;     ...
;     if (g == 0) {
;         const float m1 = MB[64 * 64], l1 = MB[65 * 64];
;         const float m = fmaxf(mrow, m1);
;         const float a0 = __builtin_amdgcn_exp2f(mrow - m), a1 = __builtin_amdgcn_exp2f(m1 - m);
;         const float inv = 1.0f / (lrow * a0 + l1 * a1);
;         const size_t tok = tokb + qr0 + r;
;         const bf16_t* gp = Z + tok * ZLD + Z_MG + h * 128 + 4 * hh;
;         bf16_t* op = OB + tok * DM + 512 + h * 128 + 4 * hh;
;         u32x2 gw[4][4];
; #pragma unroll
;         for (int i = 0; i < 4; ++i)
; #pragma unroll
;             for (int q = 0; q < 4; ++q) gw[i][q] = *(const u32x2*)(gp + i * 32 + q * 8);
; #pragma unroll
;         for (int i = 0; i < 4; ++i)
; #pragma unroll
;             for (int q = 0; q < 4; ++q) {
;                 float gv[4] = {bflo(gw[i][q].x), bfhi(gw[i][q].x), bflo(gw[i][q].y), bfhi(gw[i][q].y)}; float ov[4];
; #pragma unroll
;                 for (int e = 0; e < 4; ++e) { const float val = (o[i][q * 4 + e] * a0 + MB[(i * 16 + q * 4 + e) * 64] * a1) * inv; ov[e] = val * (gv[e] / (1.f + __expf(-gv[e]))); }
;                 *(u32x2*)(op + i * 32 + q * 8) = (u32x2){pk2(ov[0], ov[1]), pk2(ov[2], ov[3])};
.Le1_wd:
	s_xor_b32 s0, s21, 1
	s_mulk_i32 s0, 0x2200
	v_add_u32_e32 v150, s0, v104
	s_waitcnt lgkmcnt(0)
	s_barrier
	ds_read2st64_b32 v[70:71], v150 offset0:32 offset1:33
	ds_read2st64_b32 v[110:111], v150 offset0:0 offset1:1
	ds_read2st64_b32 v[112:113], v150 offset0:2 offset1:3
	ds_read2st64_b32 v[114:115], v150 offset0:4 offset1:5
	ds_read2st64_b32 v[116:117], v150 offset0:6 offset1:7
	ds_read2st64_b32 v[118:119], v150 offset0:8 offset1:9
	ds_read2st64_b32 v[120:121], v150 offset0:10 offset1:11
	ds_read2st64_b32 v[122:123], v150 offset0:12 offset1:13
	ds_read2st64_b32 v[124:125], v150 offset0:14 offset1:15
	ds_read2st64_b32 v[126:127], v150 offset0:16 offset1:17
	ds_read2st64_b32 v[128:129], v150 offset0:18 offset1:19
	ds_read2st64_b32 v[130:131], v150 offset0:20 offset1:21
	ds_read2st64_b32 v[132:133], v150 offset0:22 offset1:23
	ds_read2st64_b32 v[134:135], v150 offset0:24 offset1:25
	ds_read2st64_b32 v[136:137], v150 offset0:26 offset1:27
	ds_read2st64_b32 v[138:139], v150 offset0:28 offset1:29
	ds_read2st64_b32 v[140:141], v150 offset0:30 offset1:31
	v_max_f32_e32 v0, v204, v204
	s_lshl_b32 s0, s2, 8
	s_mov_b32 s1, s93
	v_ashrrev_i32_e32 v183, 31, v182
	s_waitcnt lgkmcnt(0)
	v_max_f32_e32 v66, v70, v70
	v_max_f32_e32 v0, v0, v66
	v_sub_f32_e32 v66, v204, v0
	v_sub_f32_e32 v0, v70, v0
	v_exp_f32_e32 v66, v66
	v_exp_f32_e32 v67, v0
	v_mov_b32_e32 v69, v71
	v_lshlrev_b32_e32 v0, 12, v202
	v_lshlrev_b64 v[102:103], 1, v[182:183]
	v_pk_mul_f32 v[68:69], v[68:69], v[66:67]
	s_mov_b64 s[4:5], 0x4600c00
	v_add_f32_e32 v105, v68, v69
	v_lshl_add_u64 v[68:69], s[50:51], 0, v[0:1]
	v_lshl_add_u64 v[70:71], v[68:69], 0, s[0:1]
	v_lshlrev_b32_e32 v0, 11, v202
	v_lshl_add_u64 v[70:71], v[70:71], 0, v[102:103]
	v_sub_co_u32_e32 v72, vcc, 0, v0
	v_lshl_add_u64 v[106:107], v[70:71], 0, s[4:5]
	s_nop 0
	v_subb_co_u32_e64 v73, s[4:5], 0, 0, vcc
	v_lshl_add_u64 v[68:69], v[68:69], 0, v[72:73]
	v_lshl_add_u64 v[68:69], v[68:69], 0, s[0:1]
	s_mov_b32 s0, 0x4600000
	v_add_co_u32_e32 v70, vcc, s0, v70
	v_div_scale_f32 v0, s[0:1], v105, v105, 1.0
	s_nop 0
	v_addc_co_u32_e32 v71, vcc, 0, v71, vcc
	s_lshl_b32 vcc_lo, s21, 7
	v_lshl_add_u32 v152, v182, 1, vcc_lo
	v_rcp_f32_e32 v106, v0
	v_lshl_add_u64 v[102:103], v[68:69], 0, v[102:103]
	s_mov_b64 s[0:1], 0xae00400
	v_lshl_add_u64 v[68:69], v[102:103], 0, s[0:1]
	v_fma_f32 v107, -v0, v106, 1.0
	v_fmac_f32_e32 v106, v107, v106
	v_div_scale_f32 v107, vcc, 1.0, v105, 1.0
	v_mul_f32_e32 v108, v107, v106
	v_fma_f32 v109, -v0, v108, v107
	v_fmac_f32_e32 v108, v109, v106
	v_fma_f32 v0, -v0, v108, v107
	v_div_fmas_f32 v0, v0, v106, v108
	v_div_fixup_f32 v0, v0, v105, 1.0
	v_mov_b32_e32 v72, v67
	v_mov_b32_e32 v153, 0
	v_lshl_add_u64 v[148:149], v[152:153], 0, v[68:69]
	s_waitcnt vmcnt(6)
	v_pk_mul_f32 v[154:155], v[72:73], v[110:111] op_sel_hi:[0,1]
	v_pk_mul_f32 v[156:157], v[72:73], v[112:113] op_sel_hi:[0,1]
	v_pk_mul_f32 v[158:159], v[72:73], v[114:115] op_sel_hi:[0,1]
	v_pk_mul_f32 v[160:161], v[72:73], v[116:117] op_sel_hi:[0,1]
	v_lshlrev_b32_e32 v162, 16, v230
	v_and_b32_e32 v163, 0xffff0000, v230
	v_lshlrev_b32_e32 v164, 16, v231
	v_and_b32_e32 v165, 0xffff0000, v231
	v_lshlrev_b32_e32 v166, 16, v232
	v_and_b32_e32 v167, 0xffff0000, v232
	v_lshlrev_b32_e32 v168, 16, v233
	v_and_b32_e32 v169, 0xffff0000, v233
	v_pk_fma_f32 v[154:155], v[50:51], v[66:67], v[154:155] op_sel_hi:[1,0,1]
	v_pk_fma_f32 v[156:157], v[52:53], v[66:67], v[156:157] op_sel_hi:[1,0,1]
	v_pk_fma_f32 v[158:159], v[54:55], v[66:67], v[158:159] op_sel_hi:[1,0,1]
	v_pk_fma_f32 v[160:161], v[56:57], v[66:67], v[160:161] op_sel_hi:[1,0,1]
	v_mul_f32_e32 v170, 0xbfb8aa3b, v162
	v_mul_f32_e32 v171, 0xbfb8aa3b, v163
	v_mul_f32_e32 v172, 0xbfb8aa3b, v164
	v_mul_f32_e32 v173, 0xbfb8aa3b, v165
	v_mul_f32_e32 v174, 0xbfb8aa3b, v166
	v_mul_f32_e32 v175, 0xbfb8aa3b, v167
	v_mul_f32_e32 v176, 0xbfb8aa3b, v168
	v_mul_f32_e32 v177, 0xbfb8aa3b, v169
	v_pk_mul_f32 v[154:155], v[0:1], v[154:155] op_sel_hi:[0,1]
	v_pk_mul_f32 v[156:157], v[0:1], v[156:157] op_sel_hi:[0,1]
	v_pk_mul_f32 v[158:159], v[0:1], v[158:159] op_sel_hi:[0,1]
	v_pk_mul_f32 v[160:161], v[0:1], v[160:161] op_sel_hi:[0,1]
	v_exp_f32_e32 v170, v170
	v_exp_f32_e32 v171, v171
	v_exp_f32_e32 v172, v172
	v_exp_f32_e32 v173, v173
	v_exp_f32_e32 v174, v174
	v_exp_f32_e32 v175, v175
	v_exp_f32_e32 v176, v176
	v_exp_f32_e32 v177, v177
	v_pk_add_f32 v[170:171], v[170:171], 1.0 op_sel_hi:[1,0]
	v_pk_add_f32 v[172:173], v[172:173], 1.0 op_sel_hi:[1,0]
	v_pk_add_f32 v[174:175], v[174:175], 1.0 op_sel_hi:[1,0]
	v_pk_add_f32 v[176:177], v[176:177], 1.0 op_sel_hi:[1,0]
	v_rcp_f32_e32 v170, v170
	v_rcp_f32_e32 v171, v171
	v_rcp_f32_e32 v172, v172
	v_rcp_f32_e32 v173, v173
	v_rcp_f32_e32 v174, v174
	v_rcp_f32_e32 v175, v175
	v_rcp_f32_e32 v176, v176
	v_rcp_f32_e32 v177, v177
	v_pk_mul_f32 v[162:163], v[162:163], v[170:171]
	v_pk_mul_f32 v[164:165], v[164:165], v[172:173]
	v_pk_mul_f32 v[166:167], v[166:167], v[174:175]
	v_pk_mul_f32 v[168:169], v[168:169], v[176:177]
	v_pk_mul_f32 v[154:155], v[162:163], v[154:155]
	v_pk_mul_f32 v[156:157], v[164:165], v[156:157]
	v_pk_mul_f32 v[158:159], v[166:167], v[158:159]
	v_pk_mul_f32 v[160:161], v[168:169], v[160:161]
	v_cvt_pk_bf16_f32 v90, v154, v155
	v_cvt_pk_bf16_f32 v91, v156, v157
	v_cvt_pk_bf16_f32 v92, v158, v159
	v_cvt_pk_bf16_f32 v93, v160, v161
	s_nop 1
	v_permlane32_swap_b32_e32 v90, v92
	v_permlane32_swap_b32_e32 v91, v93
	global_store_dwordx4 v[148:149], v[90:93], off
	s_waitcnt vmcnt(5)
; DI unsigned pk2(float lo, float hi) { f32x2 v = {lo, hi}; return __builtin_bit_cast(unsigned, __builtin_convertvector(v, bf2_t)); }
; DI float bflo(unsigned w) { return __uint_as_float(w << 16); }
; DI float bfhi(unsigned w) { return __uint_as_float(w & 0xffff0000u); }
; DI void attn_unit(const Params& p, int b, int h, int qb, LAS unsigned char* lds, int tid, int lane, int wave) {
;     ...
;             for (int q = 0; q < 4; ++q) {
;                 float gv[4] = {bflo(gw[i][q].x), bfhi(gw[i][q].x), bflo(gw[i][q].y), bfhi(gw[i][q].y)}; float ov[4];
; #pragma unroll
;                 for (int e = 0; e < 4; ++e) { const float val = (o[i][q * 4 + e] * a0 + MB[(i * 16 + q * 4 + e) * 64] * a1) * inv; ov[e] = val * (gv[e] / (1.f + __expf(-gv[e]))); }
;                 *(u32x2*)(op + i * 32 + q * 8) = (u32x2){pk2(ov[0], ov[1]), pk2(ov[2], ov[3])};
	v_pk_mul_f32 v[154:155], v[72:73], v[118:119] op_sel_hi:[0,1]
	v_pk_mul_f32 v[156:157], v[72:73], v[120:121] op_sel_hi:[0,1]
	v_pk_mul_f32 v[158:159], v[72:73], v[122:123] op_sel_hi:[0,1]
	v_pk_mul_f32 v[160:161], v[72:73], v[124:125] op_sel_hi:[0,1]
	v_lshlrev_b32_e32 v162, 16, v234
	v_and_b32_e32 v163, 0xffff0000, v234
	v_lshlrev_b32_e32 v164, 16, v235
	v_and_b32_e32 v165, 0xffff0000, v235
	v_lshlrev_b32_e32 v166, 16, v236
	v_and_b32_e32 v167, 0xffff0000, v236
	v_lshlrev_b32_e32 v168, 16, v237
	v_and_b32_e32 v169, 0xffff0000, v237
	v_pk_fma_f32 v[154:155], v[58:59], v[66:67], v[154:155] op_sel_hi:[1,0,1]
	v_pk_fma_f32 v[156:157], v[60:61], v[66:67], v[156:157] op_sel_hi:[1,0,1]
	v_pk_fma_f32 v[158:159], v[62:63], v[66:67], v[158:159] op_sel_hi:[1,0,1]
	v_pk_fma_f32 v[160:161], v[64:65], v[66:67], v[160:161] op_sel_hi:[1,0,1]
	v_mul_f32_e32 v170, 0xbfb8aa3b, v162
	v_mul_f32_e32 v171, 0xbfb8aa3b, v163
	v_mul_f32_e32 v172, 0xbfb8aa3b, v164
	v_mul_f32_e32 v173, 0xbfb8aa3b, v165
	v_mul_f32_e32 v174, 0xbfb8aa3b, v166
	v_mul_f32_e32 v175, 0xbfb8aa3b, v167
	v_mul_f32_e32 v176, 0xbfb8aa3b, v168
	v_mul_f32_e32 v177, 0xbfb8aa3b, v169
	v_pk_mul_f32 v[154:155], v[0:1], v[154:155] op_sel_hi:[0,1]
	v_pk_mul_f32 v[156:157], v[0:1], v[156:157] op_sel_hi:[0,1]
	v_pk_mul_f32 v[158:159], v[0:1], v[158:159] op_sel_hi:[0,1]
	v_pk_mul_f32 v[160:161], v[0:1], v[160:161] op_sel_hi:[0,1]
	v_exp_f32_e32 v170, v170
	v_exp_f32_e32 v171, v171
	v_exp_f32_e32 v172, v172
	v_exp_f32_e32 v173, v173
	v_exp_f32_e32 v174, v174
	v_exp_f32_e32 v175, v175
	v_exp_f32_e32 v176, v176
	v_exp_f32_e32 v177, v177
	v_pk_add_f32 v[170:171], v[170:171], 1.0 op_sel_hi:[1,0]
	v_pk_add_f32 v[172:173], v[172:173], 1.0 op_sel_hi:[1,0]
	v_pk_add_f32 v[174:175], v[174:175], 1.0 op_sel_hi:[1,0]
	v_pk_add_f32 v[176:177], v[176:177], 1.0 op_sel_hi:[1,0]
	v_rcp_f32_e32 v170, v170
	v_rcp_f32_e32 v171, v171
	v_rcp_f32_e32 v172, v172
	v_rcp_f32_e32 v173, v173
	v_rcp_f32_e32 v174, v174
	v_rcp_f32_e32 v175, v175
	v_rcp_f32_e32 v176, v176
	v_rcp_f32_e32 v177, v177
	v_pk_mul_f32 v[162:163], v[162:163], v[170:171]
	v_pk_mul_f32 v[164:165], v[164:165], v[172:173]
	v_pk_mul_f32 v[166:167], v[166:167], v[174:175]
	v_pk_mul_f32 v[168:169], v[168:169], v[176:177]
	v_pk_mul_f32 v[154:155], v[162:163], v[154:155]
	v_pk_mul_f32 v[156:157], v[164:165], v[156:157]
	v_pk_mul_f32 v[158:159], v[166:167], v[158:159]
	v_pk_mul_f32 v[160:161], v[168:169], v[160:161]
	v_cvt_pk_bf16_f32 v94, v154, v155
	v_cvt_pk_bf16_f32 v95, v156, v157
	v_cvt_pk_bf16_f32 v96, v158, v159
	v_cvt_pk_bf16_f32 v97, v160, v161
	s_nop 1
	v_permlane32_swap_b32_e32 v94, v96
	v_permlane32_swap_b32_e32 v95, v97
	global_store_dwordx4 v[148:149], v[94:97], off offset:32
	s_waitcnt vmcnt(4)
; DI unsigned pk2(float lo, float hi) { f32x2 v = {lo, hi}; return __builtin_bit_cast(unsigned, __builtin_convertvector(v, bf2_t)); }
; DI float bflo(unsigned w) { return __uint_as_float(w << 16); }
; DI float bfhi(unsigned w) { return __uint_as_float(w & 0xffff0000u); }
; DI void attn_unit(const Params& p, int b, int h, int qb, LAS unsigned char* lds, int tid, int lane, int wave) {
;     ...
;         for (int i = 0; i < 4; ++i)
; #pragma unroll
;             for (int q = 0; q < 4; ++q) {
;                 float gv[4] = {bflo(gw[i][q].x), bfhi(gw[i][q].x), bflo(gw[i][q].y), bfhi(gw[i][q].y)}; float ov[4];
; #pragma unroll
;                 for (int e = 0; e < 4; ++e) { const float val = (o[i][q * 4 + e] * a0 + MB[(i * 16 + q * 4 + e) * 64] * a1) * inv; ov[e] = val * (gv[e] / (1.f + __expf(-gv[e]))); }
;                 *(u32x2*)(op + i * 32 + q * 8) = (u32x2){pk2(ov[0], ov[1]), pk2(ov[2], ov[3])};
	v_pk_mul_f32 v[154:155], v[72:73], v[126:127] op_sel_hi:[0,1]
	v_pk_mul_f32 v[156:157], v[72:73], v[128:129] op_sel_hi:[0,1]
	v_pk_mul_f32 v[158:159], v[72:73], v[130:131] op_sel_hi:[0,1]
	v_pk_mul_f32 v[160:161], v[72:73], v[132:133] op_sel_hi:[0,1]
	v_lshlrev_b32_e32 v162, 16, v238
	v_and_b32_e32 v163, 0xffff0000, v238
	v_lshlrev_b32_e32 v164, 16, v239
	v_and_b32_e32 v165, 0xffff0000, v239
	v_lshlrev_b32_e32 v166, 16, v240
	v_and_b32_e32 v167, 0xffff0000, v240
	v_lshlrev_b32_e32 v168, 16, v241
	v_and_b32_e32 v169, 0xffff0000, v241
	v_pk_fma_f32 v[154:155], v[34:35], v[66:67], v[154:155] op_sel_hi:[1,0,1]
	v_pk_fma_f32 v[156:157], v[36:37], v[66:67], v[156:157] op_sel_hi:[1,0,1]
	v_pk_fma_f32 v[158:159], v[38:39], v[66:67], v[158:159] op_sel_hi:[1,0,1]
	v_pk_fma_f32 v[160:161], v[40:41], v[66:67], v[160:161] op_sel_hi:[1,0,1]
	v_mul_f32_e32 v170, 0xbfb8aa3b, v162
	v_mul_f32_e32 v171, 0xbfb8aa3b, v163
	v_mul_f32_e32 v172, 0xbfb8aa3b, v164
	v_mul_f32_e32 v173, 0xbfb8aa3b, v165
	v_mul_f32_e32 v174, 0xbfb8aa3b, v166
	v_mul_f32_e32 v175, 0xbfb8aa3b, v167
	v_mul_f32_e32 v176, 0xbfb8aa3b, v168
	v_mul_f32_e32 v177, 0xbfb8aa3b, v169
	v_pk_mul_f32 v[154:155], v[0:1], v[154:155] op_sel_hi:[0,1]
	v_pk_mul_f32 v[156:157], v[0:1], v[156:157] op_sel_hi:[0,1]
	v_pk_mul_f32 v[158:159], v[0:1], v[158:159] op_sel_hi:[0,1]
	v_pk_mul_f32 v[160:161], v[0:1], v[160:161] op_sel_hi:[0,1]
	v_exp_f32_e32 v170, v170
	v_exp_f32_e32 v171, v171
	v_exp_f32_e32 v172, v172
	v_exp_f32_e32 v173, v173
	v_exp_f32_e32 v174, v174
	v_exp_f32_e32 v175, v175
	v_exp_f32_e32 v176, v176
	v_exp_f32_e32 v177, v177
	v_pk_add_f32 v[170:171], v[170:171], 1.0 op_sel_hi:[1,0]
	v_pk_add_f32 v[172:173], v[172:173], 1.0 op_sel_hi:[1,0]
	v_pk_add_f32 v[174:175], v[174:175], 1.0 op_sel_hi:[1,0]
	v_pk_add_f32 v[176:177], v[176:177], 1.0 op_sel_hi:[1,0]
	v_rcp_f32_e32 v170, v170
	v_rcp_f32_e32 v171, v171
	v_rcp_f32_e32 v172, v172
	v_rcp_f32_e32 v173, v173
	v_rcp_f32_e32 v174, v174
	v_rcp_f32_e32 v175, v175
	v_rcp_f32_e32 v176, v176
	v_rcp_f32_e32 v177, v177
	v_pk_mul_f32 v[162:163], v[162:163], v[170:171]
	v_pk_mul_f32 v[164:165], v[164:165], v[172:173]
	v_pk_mul_f32 v[166:167], v[166:167], v[174:175]
	v_pk_mul_f32 v[168:169], v[168:169], v[176:177]
	v_pk_mul_f32 v[154:155], v[162:163], v[154:155]
	v_pk_mul_f32 v[156:157], v[164:165], v[156:157]
	v_pk_mul_f32 v[158:159], v[166:167], v[158:159]
	v_pk_mul_f32 v[160:161], v[168:169], v[160:161]
	v_cvt_pk_bf16_f32 v98, v154, v155
	v_cvt_pk_bf16_f32 v99, v156, v157
	v_cvt_pk_bf16_f32 v100, v158, v159
	v_cvt_pk_bf16_f32 v101, v160, v161
	s_nop 1
	v_permlane32_swap_b32_e32 v98, v100
	v_permlane32_swap_b32_e32 v99, v101
	global_store_dwordx4 v[148:149], v[98:101], off offset:64
	s_waitcnt vmcnt(3)
	v_pk_mul_f32 v[154:155], v[72:73], v[134:135] op_sel_hi:[0,1]
	v_pk_mul_f32 v[156:157], v[72:73], v[136:137] op_sel_hi:[0,1]
	v_pk_mul_f32 v[158:159], v[72:73], v[138:139] op_sel_hi:[0,1]
	v_pk_mul_f32 v[160:161], v[72:73], v[140:141] op_sel_hi:[0,1]
	v_lshlrev_b32_e32 v162, 16, v242
	v_and_b32_e32 v163, 0xffff0000, v242
	v_lshlrev_b32_e32 v164, 16, v243
	v_and_b32_e32 v165, 0xffff0000, v243
	v_lshlrev_b32_e32 v166, 16, v244
	v_and_b32_e32 v167, 0xffff0000, v244
	v_lshlrev_b32_e32 v168, 16, v245
	v_and_b32_e32 v169, 0xffff0000, v245
	v_pk_fma_f32 v[154:155], v[42:43], v[66:67], v[154:155] op_sel_hi:[1,0,1]
	v_pk_fma_f32 v[156:157], v[44:45], v[66:67], v[156:157] op_sel_hi:[1,0,1]
	v_pk_fma_f32 v[158:159], v[46:47], v[66:67], v[158:159] op_sel_hi:[1,0,1]
	v_pk_fma_f32 v[160:161], v[48:49], v[66:67], v[160:161] op_sel_hi:[1,0,1]
	v_mul_f32_e32 v170, 0xbfb8aa3b, v162
	v_mul_f32_e32 v171, 0xbfb8aa3b, v163
	v_mul_f32_e32 v172, 0xbfb8aa3b, v164
	v_mul_f32_e32 v173, 0xbfb8aa3b, v165
	v_mul_f32_e32 v174, 0xbfb8aa3b, v166
	v_mul_f32_e32 v175, 0xbfb8aa3b, v167
	v_mul_f32_e32 v176, 0xbfb8aa3b, v168
	v_mul_f32_e32 v177, 0xbfb8aa3b, v169
	v_pk_mul_f32 v[154:155], v[0:1], v[154:155] op_sel_hi:[0,1]
	v_pk_mul_f32 v[156:157], v[0:1], v[156:157] op_sel_hi:[0,1]
	v_pk_mul_f32 v[158:159], v[0:1], v[158:159] op_sel_hi:[0,1]
	v_pk_mul_f32 v[160:161], v[0:1], v[160:161] op_sel_hi:[0,1]
	v_exp_f32_e32 v170, v170
	v_exp_f32_e32 v171, v171
	v_exp_f32_e32 v172, v172
	v_exp_f32_e32 v173, v173
	v_exp_f32_e32 v174, v174
	v_exp_f32_e32 v175, v175
	v_exp_f32_e32 v176, v176
	v_exp_f32_e32 v177, v177
	v_pk_add_f32 v[170:171], v[170:171], 1.0 op_sel_hi:[1,0]
	v_pk_add_f32 v[172:173], v[172:173], 1.0 op_sel_hi:[1,0]
	v_pk_add_f32 v[174:175], v[174:175], 1.0 op_sel_hi:[1,0]
	v_pk_add_f32 v[176:177], v[176:177], 1.0 op_sel_hi:[1,0]
	v_rcp_f32_e32 v170, v170
	v_rcp_f32_e32 v171, v171
	v_rcp_f32_e32 v172, v172
	v_rcp_f32_e32 v173, v173
	v_rcp_f32_e32 v174, v174
	v_rcp_f32_e32 v175, v175
	v_rcp_f32_e32 v176, v176
	v_rcp_f32_e32 v177, v177
	v_pk_mul_f32 v[162:163], v[162:163], v[170:171]
	v_pk_mul_f32 v[164:165], v[164:165], v[172:173]
	v_pk_mul_f32 v[166:167], v[166:167], v[174:175]
	v_pk_mul_f32 v[168:169], v[168:169], v[176:177]
	v_pk_mul_f32 v[154:155], v[162:163], v[154:155]
	v_pk_mul_f32 v[156:157], v[164:165], v[156:157]
	v_pk_mul_f32 v[158:159], v[166:167], v[158:159]
	v_pk_mul_f32 v[160:161], v[168:169], v[160:161]
	v_cvt_pk_bf16_f32 v102, v154, v155
	v_cvt_pk_bf16_f32 v103, v156, v157
	v_cvt_pk_bf16_f32 v104, v158, v159
	v_cvt_pk_bf16_f32 v105, v160, v161
	s_nop 1
	v_permlane32_swap_b32_e32 v102, v104
	v_permlane32_swap_b32_e32 v103, v105
	global_store_dwordx4 v[148:149], v[102:105], off offset:96

; #define LAS __attribute__((address_space(3)))
; #define MFMA32(a, b, c) __builtin_amdgcn_mfma_f32_32x32x16_bf16((a), (b), (c), 0, 0, 0)
; #define AT_LOAD(st) do { _Pragma("unroll") for (int e = 0; e < 3; ++e) pk[e] = *(const u32x4*)(kbase + (size_t)((st) * 64 + krow[e]) * 768 + kcol[e] * 8); \
;         _Pragma("unroll") for (int e = 0; e < 2; ++e) { const int c = tid + 512 * e; pv[e] = *(const u32x4*)(vbase + (size_t)(c >> 3) * SEQ + (st) * 64 + (c & 7) * 8); } } while (0)
; DI void attn_unit(const Params& p, int b, int h, int qb, LAS unsigned char* lds, int tid, int lane, int wave) {
;     ...
;         if (st + 1 < nst) AT_LOAD(st + 1);
;         const int kb = st * 64 + g * 32;
;         if (kb <= qr0 + 31) {
;             f32x16 s;
; #pragma unroll
;             for (int j = 0; j < 16; ++j) s[j] = 0.f;
;             const LAS unsigned char* kp = lds + AT_K0 + buf * AT_KB + (g * 32 + r) * 400 + hh * 16;
;             bf16x8 kf[12];
; #pragma unroll
;             for (int kk = 0; kk < 12; ++kk) kf[kk] = *(const LAS bf16x8*)(kp + kk * 32);
;             __builtin_amdgcn_sched_barrier(0);
;             __builtin_amdgcn_s_setprio(1);
; #pragma unroll
;             for (int kk = 0; kk < 12; ++kk) s = MFMA32(kf[kk], qf[kk], s);
;             __builtin_amdgcn_s_setprio(0);
;             const LAS unsigned char* vp = lds + AT_V0 + buf * AT_VB + r * 136 + (g * 32 + 4 * hh) * 2;
;             bf16x8 vf[2][4];
; #pragma unroll
;             for (int ks = 0; ks < 2; ++ks)
; #pragma unroll
;                 for (int blk = 0; blk < 4; ++blk) {
;                     const s16x4 lo = *(const LAS s16x4*)(vp + blk * 32 * 136 + ks * 32), hi = *(const LAS s16x4*)(vp + blk * 32 * 136 + ks * 32 + 16);
;                     vf[ks][blk] = __builtin_shufflevector(lo, hi, 0, 1, 2, 3, 4, 5, 6, 7);
;                 }
;             __builtin_amdgcn_sched_barrier(0);
;             if (kb + 31 > qr0) {
;                 const int qa = qr0 + r - kb - 4 * hh;
; #pragma unroll
;                 for (int j = 0; j < 16; ++j) if ((j & 3) + 8 * (j >> 2) > qa) s[j] = -INFINITY;
;     ...
;         const bf16_t* gp = Z + tok * ZLD + Z_MG + h * 128 + 4 * hh;
;         bf16_t* op = OB + tok * DM + 512 + h * 128 + 4 * hh;
;         u32x2 gw[4][4];
; #pragma unroll
;         for (int i = 0; i < 4; ++i)
; #pragma unroll
;             for (int q = 0; q < 4; ++q) gw[i][q] = *(const u32x2*)(gp + i * 32 + q * 8);
.LBB0_452:
	v_lshlrev_b32_e32 v246, 12, v202
	s_lshl_b32 s0, s2, 8
	s_lshl_b32 s1, s21, 7
	s_add_u32 s0, s0, s1
	s_add_u32 s0, s0, 0x4600c00
	s_mov_b32 s1, s93
	v_lshl_add_u32 v246, v182, 1, v246
	v_mov_b32_e32 v247, 0
	v_lshl_add_u64 v[250:251], v[246:247], 0, s[50:51]
	v_lshl_add_u64 v[250:251], v[250:251], 0, s[0:1]
	global_load_dwordx2 v[230:231], v[250:251], off
	global_load_dwordx2 v[232:233], v[250:251], off offset:16
	global_load_dwordx2 v[234:235], v[250:251], off offset:32
	global_load_dwordx2 v[236:237], v[250:251], off offset:48
	global_load_dwordx2 v[238:239], v[250:251], off offset:64
	global_load_dwordx2 v[240:241], v[250:251], off offset:80
	global_load_dwordx2 v[242:243], v[250:251], off offset:96
	global_load_dwordx2 v[244:245], v[250:251], off offset:112
	s_add_i32 s52, s52, s53
	s_cmp_gt_i32 s52, s56
	s_cbranch_scc1 .LBB0_458
	s_and_b32 s0, s55, 1
	s_mul_i32 s1, s0, 0x6400
	v_add_u32_e32 v0, s1, v216
	ds_read_b128 v[66:69], v0
	ds_read_b128 v[130:133], v0 offset:32
	ds_read_b128 v[134:137], v0 offset:64
	ds_read_b128 v[138:141], v0 offset:96
	ds_read_b128 v[142:145], v0 offset:128
	ds_read_b128 v[146:149], v0 offset:160
	ds_read_b128 v[150:153], v0 offset:192
	ds_read_b128 v[154:157], v0 offset:224
	ds_read_b128 v[158:161], v0 offset:256
	ds_read_b128 v[162:165], v0 offset:288
	ds_read_b128 v[166:169], v0 offset:320
	ds_read_b128 v[170:173], v0 offset:352
	s_setprio 1
	s_setprio 0
	s_waitcnt lgkmcnt(11)
	v_mfma_f32_32x32x16_bf16 v[66:81], v[66:69], v[126:129], 0
	s_mulk_i32 s0, 0x4800
	v_add_u32_e32 v0, s0, v206
	s_waitcnt lgkmcnt(10)
	v_mfma_f32_32x32x16_bf16 v[66:81], v[130:133], v[122:125], v[66:81]
	s_waitcnt lgkmcnt(9)
	v_mfma_f32_32x32x16_bf16 v[66:81], v[134:137], v[118:121], v[66:81]
	s_waitcnt lgkmcnt(8)
	v_mfma_f32_32x32x16_bf16 v[66:81], v[138:141], v[114:117], v[66:81]
	s_waitcnt lgkmcnt(7)
	v_mfma_f32_32x32x16_bf16 v[66:81], v[142:145], v[110:113], v[66:81]
	s_waitcnt lgkmcnt(6)
	v_mfma_f32_32x32x16_bf16 v[66:81], v[146:149], v[106:109], v[66:81]
	s_waitcnt lgkmcnt(5)
	v_mfma_f32_32x32x16_bf16 v[66:81], v[150:153], v[102:105], v[66:81]
	s_waitcnt lgkmcnt(4)
	v_mfma_f32_32x32x16_bf16 v[66:81], v[154:157], v[98:101], v[66:81]
	s_waitcnt lgkmcnt(3)
	v_mfma_f32_32x32x16_bf16 v[66:81], v[158:161], v[94:97], v[66:81]
	s_waitcnt lgkmcnt(2)
	v_mfma_f32_32x32x16_bf16 v[66:81], v[162:165], v[90:93], v[66:81]
	ds_read_b128 v[102:105], v0 offset:51200
	ds_read_b128 v[90:93], v0 offset:51232
	ds_read_b128 v[106:109], v0 offset:55808
	s_waitcnt lgkmcnt(4)
	v_mfma_f32_32x32x16_bf16 v[66:81], v[166:169], v[86:89], v[66:81]
	ds_read_b128 v[114:117], v0 offset:60416
	ds_read_b128 v[110:113], v0 offset:65024
	ds_read_b128 v[98:101], v0 offset:55840
	ds_read_b128 v[94:97], v0 offset:60448
	ds_read_b128 v[86:89], v0 offset:65056
	s_waitcnt lgkmcnt(8)
	v_mfma_f32_32x32x16_bf16 v[66:81], v[170:173], v[82:85], v[66:81]
	s_or_b32 s0, s52, 31
	s_cmp_le_i32 s0, s36
	s_cbranch_scc1 .LBB0_455
	v_or_b32_e32 v0, s36, v205
	v_add_u32_e32 v82, s52, v182
	v_sub_u32_e32 v0, v0, v82
	v_cmp_gt_i32_e64 s[30:31], 26, v0
	v_cmp_gt_i32_e64 s[34:35], 27, v0
	v_cmp_gt_i32_e64 s[28:29], 25, v0
	s_and_b64 s[30:31], s[34:35], s[30:31]
	v_cmp_gt_i32_e64 s[26:27], 24, v0
	s_and_b64 s[28:29], s[30:31], s[28:29]
	v_cmp_gt_i32_e64 s[24:25], 19, v0
	s_and_b64 s[26:27], s[28:29], s[26:27]
	v_cmp_gt_i32_e64 s[22:23], 18, v0
	s_and_b64 s[24:25], s[26:27], s[24:25]
	v_cmp_gt_i32_e64 s[18:19], 17, v0
	s_and_b64 s[22:23], s[24:25], s[22:23]
	v_cmp_gt_i32_e64 s[16:17], 16, v0
	s_and_b64 s[18:19], s[22:23], s[18:19]
	v_cmp_gt_i32_e64 s[14:15], 11, v0
	s_and_b64 s[16:17], s[18:19], s[16:17]
	v_cmp_gt_i32_e64 s[12:13], 10, v0
	s_and_b64 s[14:15], s[16:17], s[14:15]
	v_cmp_gt_i32_e64 s[10:11], 9, v0
	s_and_b64 s[12:13], s[14:15], s[12:13]
	v_cmp_gt_i32_e64 s[8:9], 8, v0
	s_and_b64 s[10:11], s[12:13], s[10:11]
	v_cmp_gt_i32_e64 s[6:7], 3, v0
	s_and_b64 s[8:9], s[10:11], s[8:9]
	v_cmp_gt_i32_e64 s[4:5], 2, v0
	s_and_b64 s[6:7], s[8:9], s[6:7]
	v_cmp_gt_i32_e64 s[0:1], 1, v0
	s_and_b64 s[4:5], s[6:7], s[4:5]
	v_cmp_gt_i32_e32 vcc, 0, v0
	s_and_b64 s[0:1], s[4:5], s[0:1]
	s_and_b64 vcc, s[0:1], vcc
	v_cndmask_b32_e64 v81, v81, v229, s[34:35]
	v_cndmask_b32_e64 v80, v80, v229, s[30:31]
	v_cndmask_b32_e64 v79, v79, v229, s[28:29]
	v_cndmask_b32_e64 v78, v78, v229, s[26:27]
	v_cndmask_b32_e64 v77, v77, v229, s[24:25]
	v_cndmask_b32_e64 v76, v76, v229, s[22:23]
	v_cndmask_b32_e64 v75, v75, v229, s[18:19]
	v_cndmask_b32_e64 v74, v74, v229, s[16:17]
	v_cndmask_b32_e64 v73, v73, v229, s[14:15]
	v_cndmask_b32_e64 v72, v72, v229, s[12:13]
	v_cndmask_b32_e64 v71, v71, v229, s[10:11]
	v_cndmask_b32_e64 v70, v70, v229, s[8:9]
	v_cndmask_b32_e64 v69, v69, v229, s[6:7]
	v_cndmask_b32_e64 v68, v68, v229, s[4:5]
	v_cndmask_b32_e64 v67, v67, v229, s[0:1]
	v_cndmask_b32_e32 v66, v66, v229, vcc

; DI unsigned pk2(float lo, float hi) { f32x2 v = {lo, hi}; return __builtin_bit_cast(unsigned, __builtin_convertvector(v, bf2_t)); }
; DI float bflo(unsigned w) { return __uint_as_float(w << 16); }
; DI float bfhi(unsigned w) { return __uint_as_float(w & 0xffff0000u); }
; DI void attn_unit(const Params& p, int b, int h, int qb, LAS unsigned char* lds, int tid, int lane, int wave) {
;     ...
;     if (g == 0) {
;         const float m1 = MB[64 * 64], l1 = MB[65 * 64];
;         const float m = fmaxf(mrow, m1);
;         const float a0 = __builtin_amdgcn_exp2f(mrow - m), a1 = __builtin_amdgcn_exp2f(m1 - m);
;         const float inv = 1.0f / (lrow * a0 + l1 * a1);
;         const size_t tok = tokb + qr0 + r;
;         const bf16_t* gp = Z + tok * ZLD + Z_MG + h * 128 + 4 * hh;
;         bf16_t* op = OB + tok * DM + 512 + h * 128 + 4 * hh;
;         u32x2 gw[4][4];
; #pragma unroll
;         for (int i = 0; i < 4; ++i)
; #pragma unroll
;             for (int q = 0; q < 4; ++q) gw[i][q] = *(const u32x2*)(gp + i * 32 + q * 8);
; #pragma unroll
;         for (int i = 0; i < 4; ++i)
; #pragma unroll
;             for (int q = 0; q < 4; ++q) {
;                 float gv[4] = {bflo(gw[i][q].x), bfhi(gw[i][q].x), bflo(gw[i][q].y), bfhi(gw[i][q].y)}; float ov[4];
; #pragma unroll
;                 for (int e = 0; e < 4; ++e) { const float val = (o[i][q * 4 + e] * a0 + MB[(i * 16 + q * 4 + e) * 64] * a1) * inv; ov[e] = val * (gv[e] / (1.f + __expf(-gv[e]))); }
;                 *(u32x2*)(op + i * 32 + q * 8) = (u32x2){pk2(ov[0], ov[1]), pk2(ov[2], ov[3])};
.Le2_wd:
	s_xor_b32 s0, s21, 1
	s_mulk_i32 s0, 0x2200
	v_add_u32_e32 v150, s0, v104
	s_waitcnt lgkmcnt(0)
	s_barrier
	ds_read2st64_b32 v[70:71], v150 offset0:32 offset1:33
	ds_read2st64_b32 v[110:111], v150 offset0:0 offset1:1
	ds_read2st64_b32 v[112:113], v150 offset0:2 offset1:3
	ds_read2st64_b32 v[114:115], v150 offset0:4 offset1:5
	ds_read2st64_b32 v[116:117], v150 offset0:6 offset1:7
	ds_read2st64_b32 v[118:119], v150 offset0:8 offset1:9
	ds_read2st64_b32 v[120:121], v150 offset0:10 offset1:11
	ds_read2st64_b32 v[122:123], v150 offset0:12 offset1:13
	ds_read2st64_b32 v[124:125], v150 offset0:14 offset1:15
	ds_read2st64_b32 v[126:127], v150 offset0:16 offset1:17
	ds_read2st64_b32 v[128:129], v150 offset0:18 offset1:19
	ds_read2st64_b32 v[130:131], v150 offset0:20 offset1:21
	ds_read2st64_b32 v[132:133], v150 offset0:22 offset1:23
	ds_read2st64_b32 v[134:135], v150 offset0:24 offset1:25
	ds_read2st64_b32 v[136:137], v150 offset0:26 offset1:27
	ds_read2st64_b32 v[138:139], v150 offset0:28 offset1:29
	ds_read2st64_b32 v[140:141], v150 offset0:30 offset1:31
	v_max_f32_e32 v0, v204, v204
	s_lshl_b32 s92, s2, 8
	v_ashrrev_i32_e32 v183, 31, v182
	v_lshlrev_b64 v[102:103], 1, v[182:183]
	s_waitcnt lgkmcnt(0)
	v_max_f32_e32 v66, v70, v70
	v_max_f32_e32 v0, v0, v66
	v_sub_f32_e32 v66, v204, v0
	v_sub_f32_e32 v0, v70, v0
	v_exp_f32_e32 v66, v66
	v_exp_f32_e32 v67, v0
	v_mov_b32_e32 v69, v71
	v_lshlrev_b32_e32 v0, 12, v202
	s_mov_b64 s[0:1], 0x4600c00
	v_pk_mul_f32 v[68:69], v[68:69], v[66:67]
	s_nop 0
	v_add_f32_e32 v105, v68, v69
	v_lshl_add_u64 v[68:69], s[50:51], 0, v[0:1]
	v_lshl_add_u64 v[70:71], v[68:69], 0, s[92:93]
	v_lshlrev_b32_e32 v0, 11, v202
	v_lshl_add_u64 v[70:71], v[70:71], 0, v[102:103]
	v_sub_co_u32_e32 v72, vcc, 0, v0
	v_lshl_add_u64 v[106:107], v[70:71], 0, s[0:1]
	s_nop 0
	v_subb_co_u32_e64 v73, s[0:1], 0, 0, vcc
	s_mov_b32 s0, 0x4600000
	s_nop 0
	v_add_co_u32_e32 v70, vcc, s0, v70
	v_lshl_add_u64 v[68:69], v[68:69], 0, v[72:73]
	s_nop 0
	v_addc_co_u32_e32 v71, vcc, 0, v71, vcc
	s_lshl_b32 vcc_lo, s21, 7
	v_lshl_add_u32 v152, v182, 1, vcc_lo
	v_div_scale_f32 v0, s[0:1], v105, v105, 1.0
	v_rcp_f32_e32 v106, v0
	v_lshl_add_u64 v[68:69], v[68:69], 0, s[92:93]
	v_lshl_add_u64 v[102:103], v[68:69], 0, v[102:103]
	s_mov_b64 s[0:1], 0xae00400
	v_fma_f32 v107, -v0, v106, 1.0
	v_fmac_f32_e32 v106, v107, v106
	v_div_scale_f32 v107, vcc, 1.0, v105, 1.0
	v_mul_f32_e32 v108, v107, v106
	v_fma_f32 v109, -v0, v108, v107
	v_fmac_f32_e32 v108, v109, v106
	v_fma_f32 v0, -v0, v108, v107
	v_div_fmas_f32 v0, v0, v106, v108
	v_div_fixup_f32 v0, v0, v105, 1.0
	v_lshl_add_u64 v[68:69], v[102:103], 0, s[0:1]
	v_mov_b32_e32 v72, v67
	v_mov_b32_e32 v153, 0
	v_lshl_add_u64 v[148:149], v[152:153], 0, v[68:69]
	s_waitcnt vmcnt(6)
	v_pk_mul_f32 v[154:155], v[72:73], v[110:111] op_sel_hi:[0,1]
	v_pk_mul_f32 v[156:157], v[72:73], v[112:113] op_sel_hi:[0,1]
	v_pk_mul_f32 v[158:159], v[72:73], v[114:115] op_sel_hi:[0,1]
	v_pk_mul_f32 v[160:161], v[72:73], v[116:117] op_sel_hi:[0,1]
	v_lshlrev_b32_e32 v162, 16, v230
	v_and_b32_e32 v163, 0xffff0000, v230
	v_lshlrev_b32_e32 v164, 16, v231
	v_and_b32_e32 v165, 0xffff0000, v231
	v_lshlrev_b32_e32 v166, 16, v232
	v_and_b32_e32 v167, 0xffff0000, v232
	v_lshlrev_b32_e32 v168, 16, v233
	v_and_b32_e32 v169, 0xffff0000, v233
	v_pk_fma_f32 v[154:155], v[50:51], v[66:67], v[154:155] op_sel_hi:[1,0,1]
	v_pk_fma_f32 v[156:157], v[52:53], v[66:67], v[156:157] op_sel_hi:[1,0,1]
	v_pk_fma_f32 v[158:159], v[54:55], v[66:67], v[158:159] op_sel_hi:[1,0,1]
	v_pk_fma_f32 v[160:161], v[56:57], v[66:67], v[160:161] op_sel_hi:[1,0,1]
	v_mul_f32_e32 v170, 0xbfb8aa3b, v162
	v_mul_f32_e32 v171, 0xbfb8aa3b, v163
	v_mul_f32_e32 v172, 0xbfb8aa3b, v164
	v_mul_f32_e32 v173, 0xbfb8aa3b, v165
	v_mul_f32_e32 v174, 0xbfb8aa3b, v166
	v_mul_f32_e32 v175, 0xbfb8aa3b, v167
	v_mul_f32_e32 v176, 0xbfb8aa3b, v168
	v_mul_f32_e32 v177, 0xbfb8aa3b, v169
	v_pk_mul_f32 v[154:155], v[0:1], v[154:155] op_sel_hi:[0,1]
	v_pk_mul_f32 v[156:157], v[0:1], v[156:157] op_sel_hi:[0,1]
	v_pk_mul_f32 v[158:159], v[0:1], v[158:159] op_sel_hi:[0,1]
	v_pk_mul_f32 v[160:161], v[0:1], v[160:161] op_sel_hi:[0,1]
	v_exp_f32_e32 v170, v170
	v_exp_f32_e32 v171, v171
	v_exp_f32_e32 v172, v172
	v_exp_f32_e32 v173, v173
	v_exp_f32_e32 v174, v174
	v_exp_f32_e32 v175, v175
	v_exp_f32_e32 v176, v176
	v_exp_f32_e32 v177, v177
	v_pk_add_f32 v[170:171], v[170:171], 1.0 op_sel_hi:[1,0]
	v_pk_add_f32 v[172:173], v[172:173], 1.0 op_sel_hi:[1,0]
	v_pk_add_f32 v[174:175], v[174:175], 1.0 op_sel_hi:[1,0]
	v_pk_add_f32 v[176:177], v[176:177], 1.0 op_sel_hi:[1,0]
	v_rcp_f32_e32 v170, v170
	v_rcp_f32_e32 v171, v171
	v_rcp_f32_e32 v172, v172
	v_rcp_f32_e32 v173, v173
	v_rcp_f32_e32 v174, v174
	v_rcp_f32_e32 v175, v175
	v_rcp_f32_e32 v176, v176
	v_rcp_f32_e32 v177, v177
	v_pk_mul_f32 v[162:163], v[162:163], v[170:171]
	v_pk_mul_f32 v[164:165], v[164:165], v[172:173]
	v_pk_mul_f32 v[166:167], v[166:167], v[174:175]
	v_pk_mul_f32 v[168:169], v[168:169], v[176:177]
	v_pk_mul_f32 v[154:155], v[162:163], v[154:155]
	v_pk_mul_f32 v[156:157], v[164:165], v[156:157]
	v_pk_mul_f32 v[158:159], v[166:167], v[158:159]
	v_pk_mul_f32 v[160:161], v[168:169], v[160:161]
	v_cvt_pk_bf16_f32 v90, v154, v155
	v_cvt_pk_bf16_f32 v91, v156, v157
	v_cvt_pk_bf16_f32 v92, v158, v159
	v_cvt_pk_bf16_f32 v93, v160, v161
	s_nop 1
	v_permlane32_swap_b32_e32 v90, v92
	v_permlane32_swap_b32_e32 v91, v93
	global_store_dwordx4 v[148:149], v[90:93], off
	s_waitcnt vmcnt(5)
; DI unsigned pk2(float lo, float hi) { f32x2 v = {lo, hi}; return __builtin_bit_cast(unsigned, __builtin_convertvector(v, bf2_t)); }
; DI float bflo(unsigned w) { return __uint_as_float(w << 16); }
; DI float bfhi(unsigned w) { return __uint_as_float(w & 0xffff0000u); }
; DI void attn_unit(const Params& p, int b, int h, int qb, LAS unsigned char* lds, int tid, int lane, int wave) {
;     ...
;         for (int i = 0; i < 4; ++i)
; #pragma unroll
;             for (int q = 0; q < 4; ++q) {
;                 float gv[4] = {bflo(gw[i][q].x), bfhi(gw[i][q].x), bflo(gw[i][q].y), bfhi(gw[i][q].y)}; float ov[4];
; #pragma unroll
;                 for (int e = 0; e < 4; ++e) { const float val = (o[i][q * 4 + e] * a0 + MB[(i * 16 + q * 4 + e) * 64] * a1) * inv; ov[e] = val * (gv[e] / (1.f + __expf(-gv[e]))); }
;                 *(u32x2*)(op + i * 32 + q * 8) = (u32x2){pk2(ov[0], ov[1]), pk2(ov[2], ov[3])};
	v_pk_mul_f32 v[154:155], v[72:73], v[118:119] op_sel_hi:[0,1]
	v_pk_mul_f32 v[156:157], v[72:73], v[120:121] op_sel_hi:[0,1]
	v_pk_mul_f32 v[158:159], v[72:73], v[122:123] op_sel_hi:[0,1]
	v_pk_mul_f32 v[160:161], v[72:73], v[124:125] op_sel_hi:[0,1]
	v_lshlrev_b32_e32 v162, 16, v234
	v_and_b32_e32 v163, 0xffff0000, v234
	v_lshlrev_b32_e32 v164, 16, v235
	v_and_b32_e32 v165, 0xffff0000, v235
	v_lshlrev_b32_e32 v166, 16, v236
	v_and_b32_e32 v167, 0xffff0000, v236
	v_lshlrev_b32_e32 v168, 16, v237
	v_and_b32_e32 v169, 0xffff0000, v237
	v_pk_fma_f32 v[154:155], v[58:59], v[66:67], v[154:155] op_sel_hi:[1,0,1]
	v_pk_fma_f32 v[156:157], v[60:61], v[66:67], v[156:157] op_sel_hi:[1,0,1]
	v_pk_fma_f32 v[158:159], v[62:63], v[66:67], v[158:159] op_sel_hi:[1,0,1]
	v_pk_fma_f32 v[160:161], v[64:65], v[66:67], v[160:161] op_sel_hi:[1,0,1]
	v_mul_f32_e32 v170, 0xbfb8aa3b, v162
	v_mul_f32_e32 v171, 0xbfb8aa3b, v163
	v_mul_f32_e32 v172, 0xbfb8aa3b, v164
	v_mul_f32_e32 v173, 0xbfb8aa3b, v165
	v_mul_f32_e32 v174, 0xbfb8aa3b, v166
	v_mul_f32_e32 v175, 0xbfb8aa3b, v167
	v_mul_f32_e32 v176, 0xbfb8aa3b, v168
	v_mul_f32_e32 v177, 0xbfb8aa3b, v169
	v_pk_mul_f32 v[154:155], v[0:1], v[154:155] op_sel_hi:[0,1]
	v_pk_mul_f32 v[156:157], v[0:1], v[156:157] op_sel_hi:[0,1]
	v_pk_mul_f32 v[158:159], v[0:1], v[158:159] op_sel_hi:[0,1]
	v_pk_mul_f32 v[160:161], v[0:1], v[160:161] op_sel_hi:[0,1]
	v_exp_f32_e32 v170, v170
	v_exp_f32_e32 v171, v171
	v_exp_f32_e32 v172, v172
	v_exp_f32_e32 v173, v173
	v_exp_f32_e32 v174, v174
	v_exp_f32_e32 v175, v175
	v_exp_f32_e32 v176, v176
	v_exp_f32_e32 v177, v177
	v_pk_add_f32 v[170:171], v[170:171], 1.0 op_sel_hi:[1,0]
	v_pk_add_f32 v[172:173], v[172:173], 1.0 op_sel_hi:[1,0]
	v_pk_add_f32 v[174:175], v[174:175], 1.0 op_sel_hi:[1,0]
	v_pk_add_f32 v[176:177], v[176:177], 1.0 op_sel_hi:[1,0]
	v_rcp_f32_e32 v170, v170
	v_rcp_f32_e32 v171, v171
	v_rcp_f32_e32 v172, v172
	v_rcp_f32_e32 v173, v173
	v_rcp_f32_e32 v174, v174
	v_rcp_f32_e32 v175, v175
	v_rcp_f32_e32 v176, v176
	v_rcp_f32_e32 v177, v177
	v_pk_mul_f32 v[162:163], v[162:163], v[170:171]
	v_pk_mul_f32 v[164:165], v[164:165], v[172:173]
	v_pk_mul_f32 v[166:167], v[166:167], v[174:175]
	v_pk_mul_f32 v[168:169], v[168:169], v[176:177]
	v_pk_mul_f32 v[154:155], v[162:163], v[154:155]
	v_pk_mul_f32 v[156:157], v[164:165], v[156:157]
	v_pk_mul_f32 v[158:159], v[166:167], v[158:159]
	v_pk_mul_f32 v[160:161], v[168:169], v[160:161]
	v_cvt_pk_bf16_f32 v94, v154, v155
	v_cvt_pk_bf16_f32 v95, v156, v157
	v_cvt_pk_bf16_f32 v96, v158, v159
	v_cvt_pk_bf16_f32 v97, v160, v161
	s_nop 1
	v_permlane32_swap_b32_e32 v94, v96
	v_permlane32_swap_b32_e32 v95, v97
	global_store_dwordx4 v[148:149], v[94:97], off offset:32
	s_waitcnt vmcnt(4)
	v_pk_mul_f32 v[154:155], v[72:73], v[126:127] op_sel_hi:[0,1]
	v_pk_mul_f32 v[156:157], v[72:73], v[128:129] op_sel_hi:[0,1]
	v_pk_mul_f32 v[158:159], v[72:73], v[130:131] op_sel_hi:[0,1]
	v_pk_mul_f32 v[160:161], v[72:73], v[132:133] op_sel_hi:[0,1]
	v_lshlrev_b32_e32 v162, 16, v238
	v_and_b32_e32 v163, 0xffff0000, v238
	v_lshlrev_b32_e32 v164, 16, v239
	v_and_b32_e32 v165, 0xffff0000, v239
	v_lshlrev_b32_e32 v166, 16, v240
	v_and_b32_e32 v167, 0xffff0000, v240
	v_lshlrev_b32_e32 v168, 16, v241
	v_and_b32_e32 v169, 0xffff0000, v241
	v_pk_fma_f32 v[154:155], v[34:35], v[66:67], v[154:155] op_sel_hi:[1,0,1]
	v_pk_fma_f32 v[156:157], v[36:37], v[66:67], v[156:157] op_sel_hi:[1,0,1]
	v_pk_fma_f32 v[158:159], v[38:39], v[66:67], v[158:159] op_sel_hi:[1,0,1]
	v_pk_fma_f32 v[160:161], v[40:41], v[66:67], v[160:161] op_sel_hi:[1,0,1]
	v_mul_f32_e32 v170, 0xbfb8aa3b, v162
	v_mul_f32_e32 v171, 0xbfb8aa3b, v163
	v_mul_f32_e32 v172, 0xbfb8aa3b, v164
	v_mul_f32_e32 v173, 0xbfb8aa3b, v165
	v_mul_f32_e32 v174, 0xbfb8aa3b, v166
	v_mul_f32_e32 v175, 0xbfb8aa3b, v167
	v_mul_f32_e32 v176, 0xbfb8aa3b, v168
	v_mul_f32_e32 v177, 0xbfb8aa3b, v169
	v_pk_mul_f32 v[154:155], v[0:1], v[154:155] op_sel_hi:[0,1]
	v_pk_mul_f32 v[156:157], v[0:1], v[156:157] op_sel_hi:[0,1]
	v_pk_mul_f32 v[158:159], v[0:1], v[158:159] op_sel_hi:[0,1]
	v_pk_mul_f32 v[160:161], v[0:1], v[160:161] op_sel_hi:[0,1]
	v_exp_f32_e32 v170, v170
	v_exp_f32_e32 v171, v171
	v_exp_f32_e32 v172, v172
	v_exp_f32_e32 v173, v173
	v_exp_f32_e32 v174, v174
	v_exp_f32_e32 v175, v175
	v_exp_f32_e32 v176, v176
	v_exp_f32_e32 v177, v177
	v_pk_add_f32 v[170:171], v[170:171], 1.0 op_sel_hi:[1,0]
	v_pk_add_f32 v[172:173], v[172:173], 1.0 op_sel_hi:[1,0]
	v_pk_add_f32 v[174:175], v[174:175], 1.0 op_sel_hi:[1,0]
	v_pk_add_f32 v[176:177], v[176:177], 1.0 op_sel_hi:[1,0]
	v_rcp_f32_e32 v170, v170
	v_rcp_f32_e32 v171, v171
	v_rcp_f32_e32 v172, v172
	v_rcp_f32_e32 v173, v173
	v_rcp_f32_e32 v174, v174
	v_rcp_f32_e32 v175, v175
	v_rcp_f32_e32 v176, v176
	v_rcp_f32_e32 v177, v177
	v_pk_mul_f32 v[162:163], v[162:163], v[170:171]
	v_pk_mul_f32 v[164:165], v[164:165], v[172:173]
	v_pk_mul_f32 v[166:167], v[166:167], v[174:175]
	v_pk_mul_f32 v[168:169], v[168:169], v[176:177]
	v_pk_mul_f32 v[154:155], v[162:163], v[154:155]
	v_pk_mul_f32 v[156:157], v[164:165], v[156:157]
	v_pk_mul_f32 v[158:159], v[166:167], v[158:159]
	v_pk_mul_f32 v[160:161], v[168:169], v[160:161]
	v_cvt_pk_bf16_f32 v98, v154, v155
	v_cvt_pk_bf16_f32 v99, v156, v157
	v_cvt_pk_bf16_f32 v100, v158, v159
	v_cvt_pk_bf16_f32 v101, v160, v161
	s_nop 1
	v_permlane32_swap_b32_e32 v98, v100
	v_permlane32_swap_b32_e32 v99, v101
	global_store_dwordx4 v[148:149], v[98:101], off offset:64
	s_waitcnt vmcnt(3)
; DI unsigned pk2(float lo, float hi) { f32x2 v = {lo, hi}; return __builtin_bit_cast(unsigned, __builtin_convertvector(v, bf2_t)); }
; DI float bflo(unsigned w) { return __uint_as_float(w << 16); }
; DI float bfhi(unsigned w) { return __uint_as_float(w & 0xffff0000u); }
; DI void attn_unit(const Params& p, int b, int h, int qb, LAS unsigned char* lds, int tid, int lane, int wave) {
;     ...
;         for (int i = 0; i < 4; ++i)
; #pragma unroll
;             for (int q = 0; q < 4; ++q) {
;                 float gv[4] = {bflo(gw[i][q].x), bfhi(gw[i][q].x), bflo(gw[i][q].y), bfhi(gw[i][q].y)}; float ov[4];
; #pragma unroll
;                 for (int e = 0; e < 4; ++e) { const float val = (o[i][q * 4 + e] * a0 + MB[(i * 16 + q * 4 + e) * 64] * a1) * inv; ov[e] = val * (gv[e] / (1.f + __expf(-gv[e]))); }
;                 *(u32x2*)(op + i * 32 + q * 8) = (u32x2){pk2(ov[0], ov[1]), pk2(ov[2], ov[3])};
	v_pk_mul_f32 v[154:155], v[72:73], v[134:135] op_sel_hi:[0,1]
	v_pk_mul_f32 v[156:157], v[72:73], v[136:137] op_sel_hi:[0,1]
	v_pk_mul_f32 v[158:159], v[72:73], v[138:139] op_sel_hi:[0,1]
	v_pk_mul_f32 v[160:161], v[72:73], v[140:141] op_sel_hi:[0,1]
	v_lshlrev_b32_e32 v162, 16, v242
	v_and_b32_e32 v163, 0xffff0000, v242
	v_lshlrev_b32_e32 v164, 16, v243
	v_and_b32_e32 v165, 0xffff0000, v243
	v_lshlrev_b32_e32 v166, 16, v244
	v_and_b32_e32 v167, 0xffff0000, v244
	v_lshlrev_b32_e32 v168, 16, v245
	v_and_b32_e32 v169, 0xffff0000, v245
	v_pk_fma_f32 v[154:155], v[42:43], v[66:67], v[154:155] op_sel_hi:[1,0,1]
	v_pk_fma_f32 v[156:157], v[44:45], v[66:67], v[156:157] op_sel_hi:[1,0,1]
	v_pk_fma_f32 v[158:159], v[46:47], v[66:67], v[158:159] op_sel_hi:[1,0,1]
	v_pk_fma_f32 v[160:161], v[48:49], v[66:67], v[160:161] op_sel_hi:[1,0,1]
	v_mul_f32_e32 v170, 0xbfb8aa3b, v162
	v_mul_f32_e32 v171, 0xbfb8aa3b, v163
	v_mul_f32_e32 v172, 0xbfb8aa3b, v164
	v_mul_f32_e32 v173, 0xbfb8aa3b, v165
	v_mul_f32_e32 v174, 0xbfb8aa3b, v166
	v_mul_f32_e32 v175, 0xbfb8aa3b, v167
	v_mul_f32_e32 v176, 0xbfb8aa3b, v168
	v_mul_f32_e32 v177, 0xbfb8aa3b, v169
	v_pk_mul_f32 v[154:155], v[0:1], v[154:155] op_sel_hi:[0,1]
	v_pk_mul_f32 v[156:157], v[0:1], v[156:157] op_sel_hi:[0,1]
	v_pk_mul_f32 v[158:159], v[0:1], v[158:159] op_sel_hi:[0,1]
	v_pk_mul_f32 v[160:161], v[0:1], v[160:161] op_sel_hi:[0,1]
	v_exp_f32_e32 v170, v170
	v_exp_f32_e32 v171, v171
	v_exp_f32_e32 v172, v172
	v_exp_f32_e32 v173, v173
	v_exp_f32_e32 v174, v174
	v_exp_f32_e32 v175, v175
	v_exp_f32_e32 v176, v176
	v_exp_f32_e32 v177, v177
	v_pk_add_f32 v[170:171], v[170:171], 1.0 op_sel_hi:[1,0]
	v_pk_add_f32 v[172:173], v[172:173], 1.0 op_sel_hi:[1,0]
	v_pk_add_f32 v[174:175], v[174:175], 1.0 op_sel_hi:[1,0]
	v_pk_add_f32 v[176:177], v[176:177], 1.0 op_sel_hi:[1,0]
	v_rcp_f32_e32 v170, v170
	v_rcp_f32_e32 v171, v171
	v_rcp_f32_e32 v172, v172
	v_rcp_f32_e32 v173, v173
	v_rcp_f32_e32 v174, v174
	v_rcp_f32_e32 v175, v175
	v_rcp_f32_e32 v176, v176
	v_rcp_f32_e32 v177, v177
	v_pk_mul_f32 v[162:163], v[162:163], v[170:171]
	v_pk_mul_f32 v[164:165], v[164:165], v[172:173]
	v_pk_mul_f32 v[166:167], v[166:167], v[174:175]
	v_pk_mul_f32 v[168:169], v[168:169], v[176:177]
	v_pk_mul_f32 v[154:155], v[162:163], v[154:155]
	v_pk_mul_f32 v[156:157], v[164:165], v[156:157]
	v_pk_mul_f32 v[158:159], v[166:167], v[158:159]
	v_pk_mul_f32 v[160:161], v[168:169], v[160:161]
	v_cvt_pk_bf16_f32 v102, v154, v155
	v_cvt_pk_bf16_f32 v103, v156, v157
	v_cvt_pk_bf16_f32 v104, v158, v159
	v_cvt_pk_bf16_f32 v105, v160, v161
	s_nop 1
	v_permlane32_swap_b32_e32 v102, v104
	v_permlane32_swap_b32_e32 v103, v105
	global_store_dwordx4 v[148:149], v[102:105], off offset:96
	s_branch .LBB0_425
